# kv_proj and nsa_q 128-tile GEMM k-loops: fragment reads of the next k-substep issued ahead into a second register set (counted lgkmcnt)
# speedup vs baseline: 1.0059x; 1.0007x over previous
.LBB0_2049:
	s_setprio 2
	ds_read_b128 v[188:191], v134
	ds_read_b128 v[192:195], v135 offset:36864
	ds_read_b128 v[196:199], v135 offset:46080
	ds_read_b128 v[200:203], v134 offset:4608
	s_cmp_gt_u32 s1, 12
	ds_read_b128 v[224:227], v134 offset:32
	ds_read_b128 v[228:231], v135 offset:36896
	ds_read_b128 v[232:235], v135 offset:46112
	ds_read_b128 v[236:239], v134 offset:4640
	s_waitcnt lgkmcnt(6)
	v_mfma_f32_32x32x16_bf16 v[34:49], v[188:191], v[192:195], v[34:49]
	s_waitcnt lgkmcnt(5)
	v_mfma_f32_32x32x16_bf16 v[50:65], v[188:191], v[196:199], v[50:65]
	s_waitcnt lgkmcnt(4)
	v_mfma_f32_32x32x16_bf16 v[16:31], v[200:203], v[192:195], v[16:31]
	v_mfma_f32_32x32x16_bf16 v[0:15], v[200:203], v[196:199], v[0:15]
	ds_read_b128 v[188:191], v134 offset:64
	ds_read_b128 v[192:195], v135 offset:36928
	ds_read_b128 v[196:199], v135 offset:46144
	ds_read_b128 v[200:203], v134 offset:4672
	s_waitcnt lgkmcnt(6)
	v_mfma_f32_32x32x16_bf16 v[34:49], v[224:227], v[228:231], v[34:49]
	s_waitcnt lgkmcnt(5)
	v_mfma_f32_32x32x16_bf16 v[50:65], v[224:227], v[232:235], v[50:65]
	s_waitcnt lgkmcnt(4)
	v_mfma_f32_32x32x16_bf16 v[16:31], v[236:239], v[228:231], v[16:31]
	v_mfma_f32_32x32x16_bf16 v[0:15], v[236:239], v[232:235], v[0:15]
	ds_read_b128 v[224:227], v134 offset:96
	ds_read_b128 v[228:231], v135 offset:36960
	ds_read_b128 v[232:235], v135 offset:46176
	ds_read_b128 v[236:239], v134 offset:4704
	s_waitcnt lgkmcnt(6)
	v_mfma_f32_32x32x16_bf16 v[34:49], v[188:191], v[192:195], v[34:49]
	s_waitcnt lgkmcnt(5)
	v_mfma_f32_32x32x16_bf16 v[50:65], v[188:191], v[196:199], v[50:65]
	s_waitcnt lgkmcnt(4)
	v_mfma_f32_32x32x16_bf16 v[16:31], v[200:203], v[192:195], v[16:31]
	v_mfma_f32_32x32x16_bf16 v[0:15], v[200:203], v[196:199], v[0:15]
	s_waitcnt lgkmcnt(2)
	v_mfma_f32_32x32x16_bf16 v[34:49], v[224:227], v[228:231], v[34:49]
	s_waitcnt lgkmcnt(1)
	v_mfma_f32_32x32x16_bf16 v[50:65], v[224:227], v[232:235], v[50:65]
	s_setprio 0
	s_waitcnt vmcnt(7)
	ds_write_b128 v136, v[90:93] offset:18432
	s_waitcnt vmcnt(3)
	ds_write_b128 v136, v[98:101] offset:55296
	ds_write_b128 v136, v[102:105] offset:23040
	s_waitcnt vmcnt(2)
	ds_write_b128 v136, v[110:113] offset:59904
	ds_write_b128 v136, v[114:117] offset:27648
	s_waitcnt vmcnt(1)
	ds_write_b128 v136, v[118:121] offset:64512
	ds_write_b128 v136, v[122:125] offset:32256
	s_waitcnt vmcnt(0)
	ds_write_b128 v137, v[126:129] offset:13824
	s_waitcnt lgkmcnt(0)
	s_barrier
	v_mfma_f32_32x32x16_bf16 v[16:31], v[236:239], v[228:231], v[16:31]
	v_mfma_f32_32x32x16_bf16 v[0:15], v[236:239], v[232:235], v[0:15]
	s_cbranch_scc1 .LBB0_2051
	v_add_co_u32_e32 v102, vcc, 0x10000, v140
	global_load_dwordx4 v[90:93], v[140:141], off offset:384
	global_load_dwordx4 v[98:101], v[138:139], off offset:384
	v_addc_co_u32_e32 v103, vcc, 0, v141, vcc
	v_add_co_u32_e32 v110, vcc, 0x10000, v138
	global_load_dwordx4 v[102:105], v[102:103], off offset:384
	s_nop 0
	v_addc_co_u32_e32 v111, vcc, 0, v139, vcc
	v_add_co_u32_e32 v114, vcc, 0x20000, v140
	global_load_dwordx4 v[110:113], v[110:111], off offset:384
	s_nop 0
	v_addc_co_u32_e32 v115, vcc, 0, v141, vcc
	v_add_co_u32_e32 v118, vcc, 0x20000, v138
	global_load_dwordx4 v[114:117], v[114:115], off offset:384
	s_nop 0
	v_addc_co_u32_e32 v119, vcc, 0, v139, vcc
	v_add_co_u32_e32 v122, vcc, 0x30000, v140
	global_load_dwordx4 v[118:121], v[118:119], off offset:384
	s_nop 0
	v_addc_co_u32_e32 v123, vcc, 0, v141, vcc
	v_add_co_u32_e32 v126, vcc, 0x30000, v138
	global_load_dwordx4 v[122:125], v[122:123], off offset:384
	s_nop 0
	v_addc_co_u32_e32 v127, vcc, 0, v139, vcc
	global_load_dwordx4 v[126:129], v[126:127], off offset:384
.LBB0_2051:
	s_setprio 2
	ds_read_b128 v[188:191], v134 offset:18432
	ds_read_b128 v[192:195], v135 offset:55296
	ds_read_b128 v[196:199], v135 offset:64512
	ds_read_b128 v[200:203], v134 offset:23040
	s_andn2_b64 vcc, exec, s[6:7]
	ds_read_b128 v[224:227], v134 offset:18464
	ds_read_b128 v[228:231], v135 offset:55328
	ds_read_b128 v[232:235], v135 offset:64544
	ds_read_b128 v[236:239], v134 offset:23072
	s_waitcnt lgkmcnt(6)
	v_mfma_f32_32x32x16_bf16 v[34:49], v[188:191], v[192:195], v[34:49]
	s_waitcnt lgkmcnt(5)
	v_mfma_f32_32x32x16_bf16 v[50:65], v[188:191], v[196:199], v[50:65]
	s_waitcnt lgkmcnt(4)
	v_mfma_f32_32x32x16_bf16 v[16:31], v[200:203], v[192:195], v[16:31]
	v_mfma_f32_32x32x16_bf16 v[0:15], v[200:203], v[196:199], v[0:15]
	ds_read_b128 v[188:191], v134 offset:18496
	ds_read_b128 v[192:195], v135 offset:55360
	ds_read_b128 v[196:199], v135 offset:64576
	ds_read_b128 v[200:203], v134 offset:23104
	s_waitcnt lgkmcnt(6)
	v_mfma_f32_32x32x16_bf16 v[34:49], v[224:227], v[228:231], v[34:49]
	s_waitcnt lgkmcnt(5)
	v_mfma_f32_32x32x16_bf16 v[50:65], v[224:227], v[232:235], v[50:65]
	s_waitcnt lgkmcnt(4)
	v_mfma_f32_32x32x16_bf16 v[16:31], v[236:239], v[228:231], v[16:31]
	v_mfma_f32_32x32x16_bf16 v[0:15], v[236:239], v[232:235], v[0:15]
	ds_read_b128 v[224:227], v134 offset:18528
	ds_read_b128 v[228:231], v135 offset:55392
	ds_read_b128 v[232:235], v135 offset:64608
	ds_read_b128 v[236:239], v134 offset:23136
	s_waitcnt lgkmcnt(6)
	v_mfma_f32_32x32x16_bf16 v[34:49], v[188:191], v[192:195], v[34:49]
	s_waitcnt lgkmcnt(5)
	v_mfma_f32_32x32x16_bf16 v[50:65], v[188:191], v[196:199], v[50:65]
	s_waitcnt lgkmcnt(4)
	v_mfma_f32_32x32x16_bf16 v[16:31], v[200:203], v[192:195], v[16:31]
	v_mfma_f32_32x32x16_bf16 v[0:15], v[200:203], v[196:199], v[0:15]
	s_waitcnt lgkmcnt(2)
	v_mfma_f32_32x32x16_bf16 v[34:49], v[224:227], v[228:231], v[34:49]
	s_waitcnt lgkmcnt(1)
	v_mfma_f32_32x32x16_bf16 v[50:65], v[224:227], v[232:235], v[50:65]
	s_waitcnt lgkmcnt(0)
	v_mfma_f32_32x32x16_bf16 v[16:31], v[236:239], v[228:231], v[16:31]
	v_mfma_f32_32x32x16_bf16 v[0:15], v[236:239], v[232:235], v[0:15]
	s_setprio 0
	s_cbranch_vccnz .LBB0_2046
	ds_write_b128 v136, v[66:69]
	ds_write_b128 v136, v[70:73] offset:36864
	ds_write_b128 v136, v[74:77] offset:4608
	ds_write_b128 v136, v[78:81] offset:41472
	ds_write_b128 v136, v[82:85] offset:9216
	ds_write_b128 v136, v[86:89] offset:46080
	ds_write_b128 v136, v[94:97] offset:13824
	ds_write_b128 v136, v[106:109] offset:50688
	s_branch .LBB0_2046

.LBB0_2163:
	s_setprio 2
	ds_read_b128 v[188:191], v130
	ds_read_b128 v[192:195], v131 offset:36864
	ds_read_b128 v[196:199], v131 offset:46080
	ds_read_b128 v[200:203], v130 offset:4608
	s_cmp_gt_u32 s1, 28
	ds_read_b128 v[224:227], v130 offset:32
	ds_read_b128 v[228:231], v131 offset:36896
	ds_read_b128 v[232:235], v131 offset:46112
	ds_read_b128 v[236:239], v130 offset:4640
	s_waitcnt lgkmcnt(6)
	v_mfma_f32_32x32x16_bf16 v[50:65], v[188:191], v[192:195], v[50:65]
	s_waitcnt lgkmcnt(5)
	v_mfma_f32_32x32x16_bf16 v[34:49], v[188:191], v[196:199], v[34:49]
	s_waitcnt lgkmcnt(4)
	v_mfma_f32_32x32x16_bf16 v[16:31], v[200:203], v[192:195], v[16:31]
	v_mfma_f32_32x32x16_bf16 v[0:15], v[200:203], v[196:199], v[0:15]
	ds_read_b128 v[188:191], v130 offset:64
	ds_read_b128 v[192:195], v131 offset:36928
	ds_read_b128 v[196:199], v131 offset:46144
	ds_read_b128 v[200:203], v130 offset:4672
	s_waitcnt lgkmcnt(6)
	v_mfma_f32_32x32x16_bf16 v[50:65], v[224:227], v[228:231], v[50:65]
	s_waitcnt lgkmcnt(5)
	v_mfma_f32_32x32x16_bf16 v[34:49], v[224:227], v[232:235], v[34:49]
	s_waitcnt lgkmcnt(4)
	v_mfma_f32_32x32x16_bf16 v[16:31], v[236:239], v[228:231], v[16:31]
	v_mfma_f32_32x32x16_bf16 v[0:15], v[236:239], v[232:235], v[0:15]
	ds_read_b128 v[224:227], v130 offset:96
	ds_read_b128 v[228:231], v131 offset:36960
	ds_read_b128 v[232:235], v131 offset:46176
	ds_read_b128 v[236:239], v130 offset:4704
	s_waitcnt lgkmcnt(6)
	v_mfma_f32_32x32x16_bf16 v[50:65], v[188:191], v[192:195], v[50:65]
	s_waitcnt lgkmcnt(5)
	v_mfma_f32_32x32x16_bf16 v[34:49], v[188:191], v[196:199], v[34:49]
	s_waitcnt lgkmcnt(4)
	v_mfma_f32_32x32x16_bf16 v[16:31], v[200:203], v[192:195], v[16:31]
	v_mfma_f32_32x32x16_bf16 v[0:15], v[200:203], v[196:199], v[0:15]
	s_waitcnt lgkmcnt(2)
	v_mfma_f32_32x32x16_bf16 v[50:65], v[224:227], v[228:231], v[50:65]
	s_waitcnt lgkmcnt(1)
	v_mfma_f32_32x32x16_bf16 v[34:49], v[224:227], v[232:235], v[34:49]
	s_setprio 0
	s_waitcnt vmcnt(7)
	ds_write_b128 v132, v[86:89] offset:18432
	s_waitcnt vmcnt(3)
	ds_write_b128 v132, v[94:97] offset:55296
	ds_write_b128 v132, v[98:101] offset:23040
	s_waitcnt vmcnt(2)
	ds_write_b128 v132, v[106:109] offset:59904
	ds_write_b128 v132, v[110:113] offset:27648
	s_waitcnt vmcnt(1)
	ds_write_b128 v132, v[118:121] offset:64512
	ds_write_b128 v132, v[122:125] offset:32256
	s_waitcnt vmcnt(0)
	ds_write_b128 v133, v[126:129] offset:13824
	s_waitcnt lgkmcnt(0)
	s_barrier
	v_mfma_f32_32x32x16_bf16 v[16:31], v[236:239], v[228:231], v[16:31]
	v_mfma_f32_32x32x16_bf16 v[0:15], v[236:239], v[232:235], v[0:15]
	s_cbranch_scc1 .LBB0_2165
	v_add_co_u32_e32 v98, vcc, 0x10000, v140
	global_load_dwordx4 v[86:89], v[140:141], off offset:384
	global_load_dwordx4 v[94:97], v[138:139], off offset:384
	v_addc_co_u32_e32 v99, vcc, 0, v141, vcc
	v_add_co_u32_e32 v106, vcc, 0x20000, v138
	global_load_dwordx4 v[98:101], v[98:99], off offset:384
	s_nop 0
	v_addc_co_u32_e32 v107, vcc, 0, v139, vcc
	v_add_co_u32_e32 v110, vcc, 0x20000, v140
	global_load_dwordx4 v[106:109], v[106:107], off offset:384
	s_nop 0
	v_addc_co_u32_e32 v111, vcc, 0, v141, vcc
	v_add_co_u32_e32 v118, vcc, 0x40000, v138
	global_load_dwordx4 v[110:113], v[110:111], off offset:384
	s_nop 0
	v_addc_co_u32_e32 v119, vcc, 0, v139, vcc
	v_add_co_u32_e32 v122, vcc, 0x30000, v140
	global_load_dwordx4 v[118:121], v[118:119], off offset:384
	s_nop 0
	v_addc_co_u32_e32 v123, vcc, 0, v141, vcc
	v_add_co_u32_e32 v126, vcc, 0x60000, v138
	global_load_dwordx4 v[122:125], v[122:123], off offset:384
	s_nop 0
	v_addc_co_u32_e32 v127, vcc, 0, v139, vcc
	global_load_dwordx4 v[126:129], v[126:127], off offset:384
.LBB0_2165:
	s_setprio 2
	ds_read_b128 v[188:191], v130 offset:18432
	ds_read_b128 v[192:195], v131 offset:55296
	ds_read_b128 v[196:199], v131 offset:64512
	ds_read_b128 v[200:203], v130 offset:23040
	s_andn2_b64 vcc, exec, s[4:5]
	ds_read_b128 v[224:227], v130 offset:18464
	ds_read_b128 v[228:231], v131 offset:55328
	ds_read_b128 v[232:235], v131 offset:64544
	ds_read_b128 v[236:239], v130 offset:23072
	s_waitcnt lgkmcnt(6)
	v_mfma_f32_32x32x16_bf16 v[50:65], v[188:191], v[192:195], v[50:65]
	s_waitcnt lgkmcnt(5)
	v_mfma_f32_32x32x16_bf16 v[34:49], v[188:191], v[196:199], v[34:49]
	s_waitcnt lgkmcnt(4)
	v_mfma_f32_32x32x16_bf16 v[16:31], v[200:203], v[192:195], v[16:31]
	v_mfma_f32_32x32x16_bf16 v[0:15], v[200:203], v[196:199], v[0:15]
	ds_read_b128 v[188:191], v130 offset:18496
	ds_read_b128 v[192:195], v131 offset:55360
	ds_read_b128 v[196:199], v131 offset:64576
	ds_read_b128 v[200:203], v130 offset:23104
	s_waitcnt lgkmcnt(6)
	v_mfma_f32_32x32x16_bf16 v[50:65], v[224:227], v[228:231], v[50:65]
	s_waitcnt lgkmcnt(5)
	v_mfma_f32_32x32x16_bf16 v[34:49], v[224:227], v[232:235], v[34:49]
	s_waitcnt lgkmcnt(4)
	v_mfma_f32_32x32x16_bf16 v[16:31], v[236:239], v[228:231], v[16:31]
	v_mfma_f32_32x32x16_bf16 v[0:15], v[236:239], v[232:235], v[0:15]
	ds_read_b128 v[224:227], v130 offset:18528
	ds_read_b128 v[228:231], v131 offset:55392
	ds_read_b128 v[232:235], v131 offset:64608
	ds_read_b128 v[236:239], v130 offset:23136
	s_waitcnt lgkmcnt(6)
	v_mfma_f32_32x32x16_bf16 v[50:65], v[188:191], v[192:195], v[50:65]
	s_waitcnt lgkmcnt(5)
	v_mfma_f32_32x32x16_bf16 v[34:49], v[188:191], v[196:199], v[34:49]
	s_waitcnt lgkmcnt(4)
	v_mfma_f32_32x32x16_bf16 v[16:31], v[200:203], v[192:195], v[16:31]
	v_mfma_f32_32x32x16_bf16 v[0:15], v[200:203], v[196:199], v[0:15]
	s_waitcnt lgkmcnt(2)
	v_mfma_f32_32x32x16_bf16 v[50:65], v[224:227], v[228:231], v[50:65]
	s_waitcnt lgkmcnt(1)
	v_mfma_f32_32x32x16_bf16 v[34:49], v[224:227], v[232:235], v[34:49]
	s_waitcnt lgkmcnt(0)
	v_mfma_f32_32x32x16_bf16 v[16:31], v[236:239], v[228:231], v[16:31]
	v_mfma_f32_32x32x16_bf16 v[0:15], v[236:239], v[232:235], v[0:15]
	s_setprio 0
	s_cbranch_vccnz .LBB0_2160
	ds_write_b128 v132, v[66:69]
	ds_write_b128 v132, v[70:73] offset:36864
	ds_write_b128 v132, v[74:77] offset:4608
	ds_write_b128 v132, v[78:81] offset:41472
	ds_write_b128 v132, v[82:85] offset:9216
	ds_write_b128 v132, v[90:93] offset:46080
	ds_write_b128 v132, v[102:105] offset:13824
	ds_write_b128 v132, v[114:117] offset:50688
	s_branch .LBB0_2160

.LBB0_2175:
	s_setprio 2
	ds_read_b128 v[188:191], v134
	ds_read_b128 v[192:195], v135 offset:36864
	ds_read_b128 v[196:199], v135 offset:46080
	ds_read_b128 v[200:203], v134 offset:4608
	s_cmp_gt_u32 s1, 12
	ds_read_b128 v[224:227], v134 offset:32
	ds_read_b128 v[228:231], v135 offset:36896
	ds_read_b128 v[232:235], v135 offset:46112
	ds_read_b128 v[236:239], v134 offset:4640
	s_waitcnt lgkmcnt(6)
	v_mfma_f32_32x32x16_bf16 v[50:65], v[188:191], v[192:195], v[50:65]
	s_waitcnt lgkmcnt(5)
	v_mfma_f32_32x32x16_bf16 v[34:49], v[188:191], v[196:199], v[34:49]
	s_waitcnt lgkmcnt(4)
	v_mfma_f32_32x32x16_bf16 v[16:31], v[200:203], v[192:195], v[16:31]
	v_mfma_f32_32x32x16_bf16 v[0:15], v[200:203], v[196:199], v[0:15]
	ds_read_b128 v[188:191], v134 offset:64
	ds_read_b128 v[192:195], v135 offset:36928
	ds_read_b128 v[196:199], v135 offset:46144
	ds_read_b128 v[200:203], v134 offset:4672
	s_waitcnt lgkmcnt(6)
	v_mfma_f32_32x32x16_bf16 v[50:65], v[224:227], v[228:231], v[50:65]
	s_waitcnt lgkmcnt(5)
	v_mfma_f32_32x32x16_bf16 v[34:49], v[224:227], v[232:235], v[34:49]
	s_waitcnt lgkmcnt(4)
	v_mfma_f32_32x32x16_bf16 v[16:31], v[236:239], v[228:231], v[16:31]
	v_mfma_f32_32x32x16_bf16 v[0:15], v[236:239], v[232:235], v[0:15]
	ds_read_b128 v[224:227], v134 offset:96
	ds_read_b128 v[228:231], v135 offset:36960
	ds_read_b128 v[232:235], v135 offset:46176
	ds_read_b128 v[236:239], v134 offset:4704
	s_waitcnt lgkmcnt(6)
	v_mfma_f32_32x32x16_bf16 v[50:65], v[188:191], v[192:195], v[50:65]
	s_waitcnt lgkmcnt(5)
	v_mfma_f32_32x32x16_bf16 v[34:49], v[188:191], v[196:199], v[34:49]
	s_waitcnt lgkmcnt(4)
	v_mfma_f32_32x32x16_bf16 v[16:31], v[200:203], v[192:195], v[16:31]
	v_mfma_f32_32x32x16_bf16 v[0:15], v[200:203], v[196:199], v[0:15]
	s_waitcnt lgkmcnt(2)
	v_mfma_f32_32x32x16_bf16 v[50:65], v[224:227], v[228:231], v[50:65]
	s_waitcnt lgkmcnt(1)
	v_mfma_f32_32x32x16_bf16 v[34:49], v[224:227], v[232:235], v[34:49]
	s_setprio 0
	s_waitcnt vmcnt(7)
	ds_write_b128 v136, v[90:93] offset:18432
	s_waitcnt vmcnt(3)
	ds_write_b128 v136, v[98:101] offset:55296
	ds_write_b128 v136, v[102:105] offset:23040
	s_waitcnt vmcnt(2)
	ds_write_b128 v136, v[110:113] offset:59904
	ds_write_b128 v136, v[114:117] offset:27648
	s_waitcnt vmcnt(1)
	ds_write_b128 v136, v[118:121] offset:64512
	ds_write_b128 v136, v[122:125] offset:32256
	s_waitcnt vmcnt(0)
	ds_write_b128 v137, v[126:129] offset:13824
	s_waitcnt lgkmcnt(0)
	s_barrier
	v_mfma_f32_32x32x16_bf16 v[16:31], v[236:239], v[228:231], v[16:31]
	v_mfma_f32_32x32x16_bf16 v[0:15], v[236:239], v[232:235], v[0:15]
	s_cbranch_scc1 .LBB0_2177
	v_add_co_u32_e32 v102, vcc, 0x10000, v140
	global_load_dwordx4 v[90:93], v[140:141], off offset:384
	global_load_dwordx4 v[98:101], v[138:139], off offset:384
	v_addc_co_u32_e32 v103, vcc, 0, v141, vcc
	v_add_co_u32_e32 v110, vcc, 0x10000, v138
	global_load_dwordx4 v[102:105], v[102:103], off offset:384
	s_nop 0
	v_addc_co_u32_e32 v111, vcc, 0, v139, vcc
	v_add_co_u32_e32 v114, vcc, 0x20000, v140
	global_load_dwordx4 v[110:113], v[110:111], off offset:384
	s_nop 0
	v_addc_co_u32_e32 v115, vcc, 0, v141, vcc
	v_add_co_u32_e32 v118, vcc, 0x20000, v138
	global_load_dwordx4 v[114:117], v[114:115], off offset:384
	s_nop 0
	v_addc_co_u32_e32 v119, vcc, 0, v139, vcc
	v_add_co_u32_e32 v122, vcc, 0x30000, v140
	global_load_dwordx4 v[118:121], v[118:119], off offset:384
	s_nop 0
	v_addc_co_u32_e32 v123, vcc, 0, v141, vcc
	v_add_co_u32_e32 v126, vcc, 0x30000, v138
	global_load_dwordx4 v[122:125], v[122:123], off offset:384
	s_nop 0
	v_addc_co_u32_e32 v127, vcc, 0, v139, vcc
	global_load_dwordx4 v[126:129], v[126:127], off offset:384
.LBB0_2177:
	s_setprio 2
	ds_read_b128 v[188:191], v134 offset:18432
	ds_read_b128 v[192:195], v135 offset:55296
	ds_read_b128 v[196:199], v135 offset:64512
	ds_read_b128 v[200:203], v134 offset:23040
	s_andn2_b64 vcc, exec, s[6:7]
	ds_read_b128 v[224:227], v134 offset:18464
	ds_read_b128 v[228:231], v135 offset:55328
	ds_read_b128 v[232:235], v135 offset:64544
	ds_read_b128 v[236:239], v134 offset:23072
	s_waitcnt lgkmcnt(6)
	v_mfma_f32_32x32x16_bf16 v[50:65], v[188:191], v[192:195], v[50:65]
	s_waitcnt lgkmcnt(5)
	v_mfma_f32_32x32x16_bf16 v[34:49], v[188:191], v[196:199], v[34:49]
	s_waitcnt lgkmcnt(4)
	v_mfma_f32_32x32x16_bf16 v[16:31], v[200:203], v[192:195], v[16:31]
	v_mfma_f32_32x32x16_bf16 v[0:15], v[200:203], v[196:199], v[0:15]
	ds_read_b128 v[188:191], v134 offset:18496
	ds_read_b128 v[192:195], v135 offset:55360
	ds_read_b128 v[196:199], v135 offset:64576
	ds_read_b128 v[200:203], v134 offset:23104
	s_waitcnt lgkmcnt(6)
	v_mfma_f32_32x32x16_bf16 v[50:65], v[224:227], v[228:231], v[50:65]
	s_waitcnt lgkmcnt(5)
	v_mfma_f32_32x32x16_bf16 v[34:49], v[224:227], v[232:235], v[34:49]
	s_waitcnt lgkmcnt(4)
	v_mfma_f32_32x32x16_bf16 v[16:31], v[236:239], v[228:231], v[16:31]
	v_mfma_f32_32x32x16_bf16 v[0:15], v[236:239], v[232:235], v[0:15]
	ds_read_b128 v[224:227], v134 offset:18528
	ds_read_b128 v[228:231], v135 offset:55392
	ds_read_b128 v[232:235], v135 offset:64608
	ds_read_b128 v[236:239], v134 offset:23136
	s_waitcnt lgkmcnt(6)
	v_mfma_f32_32x32x16_bf16 v[50:65], v[188:191], v[192:195], v[50:65]
	s_waitcnt lgkmcnt(5)
	v_mfma_f32_32x32x16_bf16 v[34:49], v[188:191], v[196:199], v[34:49]
	s_waitcnt lgkmcnt(4)
	v_mfma_f32_32x32x16_bf16 v[16:31], v[200:203], v[192:195], v[16:31]
	v_mfma_f32_32x32x16_bf16 v[0:15], v[200:203], v[196:199], v[0:15]
	s_waitcnt lgkmcnt(2)
	v_mfma_f32_32x32x16_bf16 v[50:65], v[224:227], v[228:231], v[50:65]
	s_waitcnt lgkmcnt(1)
	v_mfma_f32_32x32x16_bf16 v[34:49], v[224:227], v[232:235], v[34:49]
	s_waitcnt lgkmcnt(0)
	v_mfma_f32_32x32x16_bf16 v[16:31], v[236:239], v[228:231], v[16:31]
	v_mfma_f32_32x32x16_bf16 v[0:15], v[236:239], v[232:235], v[0:15]
	s_setprio 0
	s_cbranch_vccnz .LBB0_2172
	ds_write_b128 v136, v[66:69]
	ds_write_b128 v136, v[70:73] offset:36864
	ds_write_b128 v136, v[74:77] offset:4608
	ds_write_b128 v136, v[78:81] offset:41472
	ds_write_b128 v136, v[82:85] offset:9216
	ds_write_b128 v136, v[86:89] offset:46080
	ds_write_b128 v136, v[94:97] offset:13824
	ds_write_b128 v136, v[106:109] offset:50688
	s_branch .LBB0_2172
